# grid barrier bodies 1-6 hand-written: non-returning top arrival, every workgroup polls the top counter
# baseline (speedup 1.0000x reference)
.LBB0_256:
	s_waitcnt vmcnt(0) lgkmcnt(0)
	v_add_u32_e32 v196, 1, v245
	s_waitcnt lgkmcnt(0)
	s_barrier
	s_and_saveexec_b64 s[0:1], s[90:91]
	s_xor_b64 s[0:1], exec, s[0:1]
	v_add_u32_e32 v196, 1, v245
	s_andn2_saveexec_b64 s[0:1], s[0:1]
	s_cbranch_execz .LBB0_318
	v_readfirstlane_b32 s6, v245
	v_readlane_b32 s4, v253, 14
	v_readlane_b32 s5, v253, 15
	v_mov_b32_e32 v1, 1
	s_add_i32 s6, s6, 1
	v_readlane_b32 s2, v253, 16
	v_readlane_b32 s3, v253, 17
	s_nop 2
	global_atomic_add v0, v195, v1, s[4:5] sc0
	s_mul_i32 s7, s6, s77
	s_waitcnt vmcnt(0)
	v_readfirstlane_b32 s4, v0
	s_add_i32 s4, s4, 1
	s_cmp_eq_u32 s4, s7
	s_cbranch_scc0 .Lgb1_poll
	buffer_wbl2 sc1
	s_waitcnt vmcnt(0)
	global_atomic_add v195, v1, s[2:3]
.Lgb1_poll:
	v_readlane_b32 s5, v253, 2
	s_movk_i32 s7, 0x800
	s_mul_i32 s5, s6, s5
.Lgb1_spin:
	global_load_dword v0, v195, s[2:3] sc1
	s_waitcnt vmcnt(0)
	v_readfirstlane_b32 s4, v0
	s_cmp_ge_u32 s4, s5
	s_cbranch_scc1 .Lgb1_rel
	s_sleep 1
	s_sub_u32 s7, s7, 1
	s_cmp_lg_u32 s7, 0
	s_cbranch_scc1 .Lgb1_spin
.Lgb1_rel:
	buffer_inv sc1
	s_waitcnt vmcnt(0)

.LBB0_366:
	s_waitcnt vmcnt(0) lgkmcnt(0)
	v_add_u32_e32 v109, 2, v245
	s_barrier
	s_and_saveexec_b64 s[0:1], s[90:91]
	s_xor_b64 s[0:1], exec, s[0:1]
	v_add_u32_e32 v109, 2, v245
	s_andn2_saveexec_b64 s[0:1], s[0:1]
	s_cbranch_execz .LBB0_428
	v_readfirstlane_b32 s6, v245
	v_readlane_b32 s4, v253, 14
	v_readlane_b32 s5, v253, 15
	v_mov_b32_e32 v1, 1
	s_add_i32 s6, s6, 2
	v_readlane_b32 s2, v253, 16
	v_readlane_b32 s3, v253, 17
	s_nop 2
	global_atomic_add v0, v195, v1, s[4:5] sc0
	s_mul_i32 s7, s6, s77
	s_waitcnt vmcnt(0)
	v_readfirstlane_b32 s4, v0
	s_add_i32 s4, s4, 1
	s_cmp_eq_u32 s4, s7
	s_cbranch_scc0 .Lgb2_poll
	buffer_wbl2 sc1
	s_waitcnt vmcnt(0)
	global_atomic_add v195, v1, s[2:3]

.Lgmlp_done:
.LBB0_605:
	s_waitcnt vmcnt(0) lgkmcnt(0)
	v_add_u32_e32 v41, 3, v245
	s_waitcnt vmcnt(0) lgkmcnt(0)
	s_barrier
	s_and_saveexec_b64 s[0:1], s[90:91]
	s_xor_b64 s[0:1], exec, s[0:1]
	v_add_u32_e32 v41, 3, v245
	s_or_saveexec_b64 s[0:1], s[0:1]
	v_readlane_b32 s97, v255, 27
	s_xor_b64 exec, exec, s[0:1]
	s_cbranch_execz .LBB0_667
	v_readfirstlane_b32 s6, v245
	v_readlane_b32 s4, v253, 14
	v_readlane_b32 s5, v253, 15
	v_mov_b32_e32 v1, 1
	s_add_i32 s6, s6, 3
	v_readlane_b32 s2, v253, 16
	v_readlane_b32 s3, v253, 17
	s_nop 2
	global_atomic_add v0, v195, v1, s[4:5] sc0
	s_mul_i32 s7, s6, s77
	s_waitcnt vmcnt(0)
	v_readfirstlane_b32 s4, v0
	s_add_i32 s4, s4, 1
	s_cmp_eq_u32 s4, s7
	s_cbranch_scc0 .Lgb3_poll
	buffer_wbl2 sc1
	s_waitcnt vmcnt(0)
	global_atomic_add v195, v1, s[2:3]

.LBB0_687:
	s_waitcnt vmcnt(0) lgkmcnt(0)
	v_add_u32_e32 v193, 4, v245
	s_waitcnt lgkmcnt(0)
	s_barrier
	s_and_saveexec_b64 s[0:1], s[90:91]
	s_xor_b64 s[0:1], exec, s[0:1]
	v_add_u32_e32 v193, 4, v245
	s_andn2_saveexec_b64 s[0:1], s[0:1]
	s_cbranch_execz .LBB0_749
	v_readfirstlane_b32 s6, v245
	v_readlane_b32 s4, v253, 14
	v_readlane_b32 s5, v253, 15
	v_mov_b32_e32 v1, 1
	s_add_i32 s6, s6, 4
	v_readlane_b32 s2, v253, 16
	v_readlane_b32 s3, v253, 17
	s_nop 2
	global_atomic_add v0, v195, v1, s[4:5] sc0
	s_mul_i32 s7, s6, s77
	s_waitcnt vmcnt(0)
	v_readfirstlane_b32 s4, v0
	s_add_i32 s4, s4, 1
	s_cmp_eq_u32 s4, s7
	s_cbranch_scc0 .Lgb4_poll
	buffer_wbl2 sc1
	s_waitcnt vmcnt(0)
	global_atomic_add v195, v1, s[2:3]

.LBB0_792:
	s_waitcnt vmcnt(0) lgkmcnt(0)
	v_add_u32_e32 v157, 5, v245
	s_waitcnt lgkmcnt(0)
	s_barrier
	s_and_saveexec_b64 s[0:1], s[90:91]
	s_xor_b64 s[0:1], exec, s[0:1]
	v_add_u32_e32 v157, 5, v245
	s_andn2_saveexec_b64 s[0:1], s[0:1]
	s_cbranch_execz .LBB0_854
	v_readfirstlane_b32 s6, v245
	v_readlane_b32 s4, v253, 14
	v_readlane_b32 s5, v253, 15
	v_mov_b32_e32 v1, 1
	s_add_i32 s6, s6, 5
	v_readlane_b32 s2, v253, 16
	v_readlane_b32 s3, v253, 17
	s_nop 2
	global_atomic_add v0, v195, v1, s[4:5] sc0
	s_mul_i32 s7, s6, s77
	s_waitcnt vmcnt(0)
	v_readfirstlane_b32 s4, v0
	s_add_i32 s4, s4, 1
	s_cmp_eq_u32 s4, s7
	s_cbranch_scc0 .Lgb5_poll
	buffer_wbl2 sc1
	s_waitcnt vmcnt(0)
	global_atomic_add v195, v1, s[2:3]

.LBB0_984:
	s_waitcnt vmcnt(0) lgkmcnt(0)
	v_add_u32_e32 v193, 6, v245
	s_waitcnt lgkmcnt(0)
	s_barrier
	s_and_saveexec_b64 s[0:1], s[90:91]
	s_xor_b64 s[0:1], exec, s[0:1]
	v_add_u32_e32 v193, 6, v245
	s_andn2_saveexec_b64 s[0:1], s[0:1]
	s_cbranch_execz .LBB0_1046
	v_readfirstlane_b32 s6, v245
	v_readlane_b32 s4, v253, 14
	v_readlane_b32 s5, v253, 15
	v_mov_b32_e32 v1, 1
	s_add_i32 s6, s6, 6
	v_readlane_b32 s2, v253, 16
	v_readlane_b32 s3, v253, 17
	s_nop 2
	global_atomic_add v0, v195, v1, s[4:5] sc0
	s_mul_i32 s7, s6, s77
	s_waitcnt vmcnt(0)
	v_readfirstlane_b32 s4, v0
	s_add_i32 s4, s4, 1
	s_cmp_eq_u32 s4, s7
	s_cbranch_scc0 .Lgb6_poll
	buffer_wbl2 sc1
	s_waitcnt vmcnt(0)
	global_atomic_add v195, v1, s[2:3]

.Lgb6_rel:
	buffer_inv sc1
	v_readlane_b32 s4, v253, 18
	v_readlane_b32 s5, v253, 19
	v_mov_b32_e32 v1, s6
	s_nop 4
	global_atomic_umax v195, v1, s[4:5]
	s_waitcnt vmcnt(0)
